# v33 + s_setprio 3 around the LDS-DMA issue block in ffn_in and gemm_res K=2816 k-loop heads
# speedup vs baseline: 1.0185x; 1.0147x over previous
; DEVI void glds_tile8(const unsigned (&va)[4], const unsigned (&vb)[4], const void* sa, const void* sb, unsigned lds) {
;     ...
;     asm volatile(
;         "s_mov_b32 %[keep], m0\n\t"
;         "s_mov_b32 m0, %[l]\n\ts_nop 0\n\tglobal_load_lds_dwordx4 %[a0], %[sa]\n\t"
;         "s_add_u32 m0, m0, 0x1000\n\ts_nop 0\n\tglobal_load_lds_dwordx4 %[a1], %[sa]\n\t"
;         "s_add_u32 m0, m0, 0x1000\n\ts_nop 0\n\tglobal_load_lds_dwordx4 %[a2], %[sa]\n\t"
;         "s_add_u32 m0, m0, 0x1000\n\ts_nop 0\n\tglobal_load_lds_dwordx4 %[a3], %[sa]\n\t"
;         "s_add_u32 m0, m0, 0x1000\n\ts_nop 0\n\tglobal_load_lds_dwordx4 %[b0], %[sb]\n\t"
;         "s_add_u32 m0, m0, 0x1000\n\ts_nop 0\n\tglobal_load_lds_dwordx4 %[b1], %[sb]\n\t"
;         "s_add_u32 m0, m0, 0x1000\n\ts_nop 0\n\tglobal_load_lds_dwordx4 %[b2], %[sb]\n\t"
;         "s_add_u32 m0, m0, 0x1000\n\ts_nop 0\n\tglobal_load_lds_dwordx4 %[b3], %[sb]\n\t"
;         "s_mov_b32 m0, %[keep]"
;         : [keep] "=&s"(keep)
;         : [a0] "v"(va[0]), [a1] "v"(va[1]), [a2] "v"(va[2]), [a3] "v"(va[3]), [b0] "v"(vb[0]), [b1] "v"(vb[1]), [b2] "v"(vb[2]), [b3] "v"(vb[3]),
;           [sa] "s"(sa), [sb] "s"(sb), [l] "s"(lds)
;         : "memory", "scc");
;     ...
;     auto issue = [&](int kt, int st) {
;         glds_tile8(va, vb, a0p + (size_t)kt * kstepA, Btile + (size_t)kt * 64, __builtin_amdgcn_readfirstlane(lds0 + st * 32768));
;     };
;     const int sw0 = (quad ^ (l16 >> 1)) * 16;
;     const int aoffb = (wr * 64 + l16) * 128, boffb = 16384 + (wc * 64 + l16) * 128;
;     if (!first_issued) issue(0, 0);
; #pragma unroll 1
;     for (int kt = 0; kt < nk; ++kt) {
;         asm volatile("s_waitcnt vmcnt(0)\n\ts_barrier" ::: "memory");
;         if (kt + 1 < nk) issue(kt + 1, (kt + 1) & 1);
.LBB0_758:
	s_add_i32 s66, s65, 0x8000
	s_and_b32 s40, s66, 0x8000
	s_add_i32 s40, s47, s40
	s_cmp_lt_u32 s64, 43
	s_waitcnt vmcnt(0)
	s_barrier
	s_cbranch_scc0 .LBB0_757
	s_setprio 3
	s_mov_b32 s41, m0
	s_mov_b32 m0, s40
	s_nop 0
	global_load_lds_dwordx4 v0, s[38:39]
	s_add_u32 m0, m0, 0x1000
	s_nop 0
	global_load_lds_dwordx4 v70, s[38:39]
	s_add_u32 m0, m0, 0x1000
	s_nop 0
	global_load_lds_dwordx4 v71, s[38:39]
	s_add_u32 m0, m0, 0x1000
	s_nop 0
	global_load_lds_dwordx4 v72, s[38:39]
	s_add_u32 m0, m0, 0x1000
	s_nop 0
	global_load_lds_dwordx4 v0, s[34:35]
	s_add_u32 m0, m0, 0x1000
	s_nop 0
	global_load_lds_dwordx4 v70, s[34:35]
	s_add_u32 m0, m0, 0x1000
	s_nop 0
	global_load_lds_dwordx4 v71, s[34:35]
	s_add_u32 m0, m0, 0x1000
	s_nop 0
	global_load_lds_dwordx4 v72, s[34:35]
	s_mov_b32 m0, s41
	s_setprio 0
	s_branch .LBB0_757

; DEVI void glds_tile8(const unsigned (&va)[4], const unsigned (&vb)[4], const void* sa, const void* sb, unsigned lds) {
;     ...
;     asm volatile(
;         "s_mov_b32 %[keep], m0\n\t"
;         "s_mov_b32 m0, %[l]\n\ts_nop 0\n\tglobal_load_lds_dwordx4 %[a0], %[sa]\n\t"
;         "s_add_u32 m0, m0, 0x1000\n\ts_nop 0\n\tglobal_load_lds_dwordx4 %[a1], %[sa]\n\t"
;         "s_add_u32 m0, m0, 0x1000\n\ts_nop 0\n\tglobal_load_lds_dwordx4 %[a2], %[sa]\n\t"
;         "s_add_u32 m0, m0, 0x1000\n\ts_nop 0\n\tglobal_load_lds_dwordx4 %[a3], %[sa]\n\t"
;         "s_add_u32 m0, m0, 0x1000\n\ts_nop 0\n\tglobal_load_lds_dwordx4 %[b0], %[sb]\n\t"
;         "s_add_u32 m0, m0, 0x1000\n\ts_nop 0\n\tglobal_load_lds_dwordx4 %[b1], %[sb]\n\t"
;         "s_add_u32 m0, m0, 0x1000\n\ts_nop 0\n\tglobal_load_lds_dwordx4 %[b2], %[sb]\n\t"
;         "s_add_u32 m0, m0, 0x1000\n\ts_nop 0\n\tglobal_load_lds_dwordx4 %[b3], %[sb]\n\t"
;         "s_mov_b32 m0, %[keep]"
;         : [keep] "=&s"(keep)
;         : [a0] "v"(va[0]), [a1] "v"(va[1]), [a2] "v"(va[2]), [a3] "v"(va[3]), [b0] "v"(vb[0]), [b1] "v"(vb[1]), [b2] "v"(vb[2]), [b3] "v"(vb[3]),
;           [sa] "s"(sa), [sb] "s"(sb), [l] "s"(lds)
;         : "memory", "scc");
;     ...
;     auto issue = [&](int kt, int st) {
;         glds_tile8(va, vb, a0p + (size_t)kt * kstepA, Btile + (size_t)kt * 64, __builtin_amdgcn_readfirstlane(lds0 + st * 32768));
;     };
;     const int sw0 = (quad ^ (l16 >> 1)) * 16;
;     const int aoffb = (wr * 64 + l16) * 128, boffb = 16384 + (wc * 64 + l16) * 128;
;     if (!first_issued) issue(0, 0);
; #pragma unroll 1
;     for (int kt = 0; kt < nk; ++kt) {
;         asm volatile("s_waitcnt vmcnt(0)\n\ts_barrier" ::: "memory");
;         if (kt + 1 < nk) issue(kt + 1, (kt + 1) & 1);
.Lffn_bar2:
	s_cmp_lg_u32 s31, 0x78000
	s_barrier
	s_cbranch_scc0 .LBB0_788
	s_setprio 3
	s_mov_b32 s25, m0
	s_mov_b32 m0, s24
	s_nop 0
	global_load_lds_dwordx4 v0, s[14:15]
	s_add_u32 m0, m0, 0x1000
	s_nop 0
	global_load_lds_dwordx4 v68, s[14:15]
	s_add_u32 m0, m0, 0x1000
	s_nop 0
	global_load_lds_dwordx4 v69, s[14:15]
	s_add_u32 m0, m0, 0x1000
	s_nop 0
	global_load_lds_dwordx4 v71, s[14:15]
	s_add_u32 m0, m0, 0x1000
	s_nop 0
	global_load_lds_dwordx4 v0, s[10:11]
	s_add_u32 m0, m0, 0x1000
	s_nop 0
	global_load_lds_dwordx4 v68, s[10:11]
	s_add_u32 m0, m0, 0x1000
	s_nop 0
	global_load_lds_dwordx4 v69, s[10:11]
	s_add_u32 m0, m0, 0x1000
	s_nop 0
	global_load_lds_dwordx4 v71, s[10:11]
	s_mov_b32 m0, s25
	s_setprio 0
	s_branch .LBB0_788
